# stack: all 10 peelable K-loops peeled (incl. second SSM GEMM) + load-segment s_nop diet on top of the scalar-base staging / hoisted B-read / young-epilogue-priority version
# speedup vs baseline: 1.0141x; 1.0115x over previous
;     ...
;     f32x4 acc[2][2][4][2];
; #pragma unroll
;     for (int a = 0; a < 2; ++a)
; #pragma unroll
;         for (int b = 0; b < 2; ++b)
; #pragma unroll
;             for (int m = 0; m < 4; ++m)
; #pragma unroll
;                 for (int n = 0; n < 2; ++n) acc[a][b][m][n] = (f32x4){0.f, 0.f, 0.f, 0.f};
;     bf16x8 At[4][2], B0[2][2], B1[2][2];
;     const char* cA = cur.A; const char* cB = cur.B;
;     G_STAGE(G_SB(0, 0), cB, cB0, qB); G_STAGE(G_SA(0, 0), cA, cA0, qA); G_STAGE(G_SB(0, 1), cB + chB, cB0, qB); G_STAGE(G_SA(0, 1), cA + chA, cA0, qA);
;     if (wr == 1) G_BAR;
;     G_WAIT_V(4); G_BAR;
;     G_STAGE(G_SB(1, 0), cB + kB, cB0, qB); G_STAGE(G_SA(1, 0), cA + ckA, cA0, qA); G_STAGE(G_SB(1, 1), cB + chB + kB, cB0, qB);
;     G_WAIT_V(6); G_BAR;
;     for (;;) {
;         const bool has_next = sched_next<PH, SUB>(E.ws, E.layer, ui + 1, nxt, E.x);
;         if (!has_next) nxt = cur;
;         const char* nA = nxt.A; const char* nB = nxt.B;
; #pragma unroll 1
;         for (int t = 0; t < nt; t += 2) {
;             const bool last = (t == nt - 2);
;             const char* a1 = cA + (size_t)(t + 1) * ckA;
;             const char* a2 = last ? nA : cA + (size_t)(t + 2) * ckA; const char* b2 = last ? nB : cB + (size_t)(t + 2) * kB;
;             const char* a3 = a2 + ckA; const char* b3 = b2 + kB;
;             G_LDB(B0, 0, 0); G_SCHED; G_LDA(At, 0, 0); G_STAGE(G_SA(1, 1), a1 + chA, cA0, qA);
;             G_WAIT_L(8); G_BAR; G_WAIT_L(0); G_MMA(0, 0, At, B0); G_BAR; G_SCHED;
;             G_LDB(B1, 0, 1); G_STAGE(G_SB(0, 0), b2, cB0, qB);
;             G_BAR; G_WAIT_L(0); G_MMA(0, 1, At, B1); G_BAR;
;             G_LDA(At, 0, 1); G_STAGE(G_SA(0, 0), a2, cA0, qA);
;             G_BAR; G_WAIT_L(0); G_MMA(1, 0, At, B0); G_BAR; G_SCHED;
;             G_STAGE(G_SB(0, 1), b2 + chB, cB0, qB);
;             G_WAIT_V(6); G_BAR; G_MMA(1, 1, At, B1); G_BAR;
;             G_LDB(B0, 1, 0); G_SCHED; G_LDA(At, 1, 0); G_STAGE(G_SA(0, 1), a2 + chA, cA0, qA);
;             G_WAIT_L(8); G_BAR; G_WAIT_L(0); G_MMA(0, 0, At, B0); G_BAR; G_SCHED;
;             G_LDB(B1, 1, 1); G_STAGE(G_SB(1, 0), b3, cB0, qB);
;             G_BAR; G_WAIT_L(0); G_MMA(0, 1, At, B1); G_BAR;
;             G_LDA(At, 1, 1); G_STAGE(G_SA(1, 0), a3, cA0, qA);
;             G_BAR; G_WAIT_L(0); G_MMA(1, 0, At, B0); G_BAR; G_SCHED;
;             G_STAGE(G_SB(1, 1), b3 + chB, cB0, qB);
.LBB0_741:
	s_mov_b64 s[30:31], 0
	s_mov_b64 s[24:25], -1
	s_mov_b64 s[26:27], 0
	s_mov_b64 s[82:83], 0x10000
	s_mov_b64 s[84:85], 0x10080
	s_mov_b64 s[86:87], 0x200000
	s_mov_b64 s[88:89], 0x100000
	s_mov_b64 s[92:93], 0x8000
	s_mov_b64 s[94:95], 0x18000
	s_mov_b64 s[96:97], 0x300000
	s_mov_b64 s[70:71], 0x8080
	s_mov_b64 s[68:69], 0x100080
	s_mov_b64 s[28:29], 0x18080
	s_cmp_eq_u32 s101, 2
	s_cselect_b32 s101, 0, s101
	s_setprio 0
	v_add_u32_e32 v255, 0x10000, v183
	s_add_u32 s36, s2, s30
	s_addc_u32 s37, s3, s31
	s_add_u32 s19, s36, 0x100
	s_addc_u32 s35, s37, 0
	s_and_b64 s[4:5], s[26:27], exec
	s_cselect_b32 s34, s12, s19
	s_cselect_b32 s35, s13, s35
	s_add_u32 s4, s20, s30
	s_addc_u32 s5, s21, s31
	s_add_u32 s19, s4, 0x100
	s_addc_u32 s30, s5, 0
	s_add_i32 s44, 0, 0x10000
	ds_read_b128 v[56:59], v255 offset:0
	ds_read_b128 v[60:63], v255 offset:1024
	ds_read_b128 v[144:147], v255 offset:2048
	ds_read_b128 v[148:151], v255 offset:3072
	s_and_b64 s[4:5], s[26:27], exec
	s_cselect_b32 s26, s16, s19
	s_cselect_b32 s27, s17, s30
	s_add_i32 s48, 0, 0x14000
	s_add_i32 s31, 0, 0x18000
	s_add_i32 s19, 0, 0x1c000
	s_add_i32 s49, s44, s38
	s_add_i32 s63, s48, s38
	s_add_i32 s30, s31, s38
	s_add_i32 s65, s19, s38
	s_add_i32 m0, s43, 0xc000
	s_add_i32 s45, s43, 0xe000
	s_add_i32 s66, s49, 0x2000
	s_add_i32 s62, s63, 0x2000
	s_add_i32 s67, s30, 0x2000
	s_add_i32 s64, s65, 0x2000
	s_mov_b64 s[4:5], 0x200080
	s_add_u32 vcc_lo, s36, s4
	s_addc_u32 vcc_hi, s37, s5
	s_mov_b64 s[4:5], 0x300080
	ds_read_b128 v[152:155], v184
	ds_read_b128 v[156:159], v184 offset:1024
	ds_read_b128 v[162:165], v184 offset:2048
	ds_read_b128 v[172:175], v184 offset:3072
	ds_read_b128 v[176:179], v184 offset:4096
	ds_read_b128 v[196:199], v184 offset:5120
	ds_read_b128 v[200:203], v184 offset:6144
	ds_read_b128 v[204:207], v184 offset:7168
	global_load_lds_dwordx4 v160, vcc
	s_mov_b32 m0, s45
	s_add_u32 vcc_lo, s36, s4
	s_addc_u32 vcc_hi, s37, s5
	global_load_lds_dwordx4 v160, vcc
	s_waitcnt lgkmcnt(8)
	s_cmp_eq_u32 s101, 1
	s_cbranch_scc1 .Ldb_SSM2_skp
	s_barrier
.Ldb_SSM2_skp:
	s_mov_b32 s101, 0
	s_waitcnt lgkmcnt(0)
	v_mfma_f32_16x16x32_bf16 v[140:143], v[56:59], v[152:155], 0
	v_mfma_f32_16x16x32_bf16 v[136:139], v[144:147], v[152:155], 0
	v_mfma_f32_16x16x32_bf16 v[124:127], v[56:59], v[162:165], 0
	v_mfma_f32_16x16x32_bf16 v[120:123], v[144:147], v[162:165], 0
	v_mfma_f32_16x16x32_bf16 v[108:111], v[56:59], v[176:179], 0
	v_mfma_f32_16x16x32_bf16 v[104:107], v[144:147], v[176:179], 0
	v_mfma_f32_16x16x32_bf16 v[92:95], v[56:59], v[200:203], 0
	v_mfma_f32_16x16x32_bf16 v[88:91], v[144:147], v[200:203], 0
	v_mfma_f32_16x16x32_bf16 v[140:143], v[60:63], v[156:159], v[140:143]
	v_mfma_f32_16x16x32_bf16 v[136:139], v[148:151], v[156:159], v[136:139]
	v_mfma_f32_16x16x32_bf16 v[124:127], v[60:63], v[172:175], v[124:127]
	v_mfma_f32_16x16x32_bf16 v[120:123], v[148:151], v[172:175], v[120:123]
	v_mfma_f32_16x16x32_bf16 v[108:111], v[60:63], v[196:199], v[108:111]
	v_mfma_f32_16x16x32_bf16 v[104:107], v[148:151], v[196:199], v[104:107]
	v_mfma_f32_16x16x32_bf16 v[92:95], v[60:63], v[204:207], v[92:95]
	v_mfma_f32_16x16x32_bf16 v[88:91], v[148:151], v[204:207], v[88:91]
	s_barrier
	s_mov_b32 m0, s49
	ds_read_b128 v[208:211], v255 offset:16384
	ds_read_b128 v[212:215], v255 offset:17408
	ds_read_b128 v[216:219], v255 offset:18432
	ds_read_b128 v[220:223], v255 offset:19456
	global_load_lds_dwordx4 v2, s[26:27]
	s_mov_b32 m0, s66
	s_add_u32 vcc_lo, s26, s92
	s_addc_u32 vcc_hi, s27, s93
	global_load_lds_dwordx4 v2, vcc
	s_barrier
	s_waitcnt lgkmcnt(0)
	v_mfma_f32_16x16x32_bf16 v[132:135], v[208:211], v[152:155], 0
	v_mfma_f32_16x16x32_bf16 v[128:131], v[216:219], v[152:155], 0
	v_mfma_f32_16x16x32_bf16 v[116:119], v[208:211], v[162:165], 0
	v_mfma_f32_16x16x32_bf16 v[112:115], v[216:219], v[162:165], 0
	v_mfma_f32_16x16x32_bf16 v[100:103], v[208:211], v[176:179], 0
	v_mfma_f32_16x16x32_bf16 v[96:99], v[216:219], v[176:179], 0
	v_mfma_f32_16x16x32_bf16 v[84:87], v[208:211], v[200:203], 0
	v_mfma_f32_16x16x32_bf16 v[80:83], v[216:219], v[200:203], 0
	v_mfma_f32_16x16x32_bf16 v[132:135], v[212:215], v[156:159], v[132:135]
	v_mfma_f32_16x16x32_bf16 v[128:131], v[220:223], v[156:159], v[128:131]
	v_mfma_f32_16x16x32_bf16 v[116:119], v[212:215], v[172:175], v[116:119]
	v_mfma_f32_16x16x32_bf16 v[112:115], v[220:223], v[172:175], v[112:115]
	v_mfma_f32_16x16x32_bf16 v[100:103], v[212:215], v[196:199], v[100:103]
	v_mfma_f32_16x16x32_bf16 v[96:99], v[220:223], v[196:199], v[96:99]
	v_mfma_f32_16x16x32_bf16 v[84:87], v[212:215], v[204:207], v[84:87]
	v_mfma_f32_16x16x32_bf16 v[80:83], v[220:223], v[204:207], v[80:83]
	s_barrier
	s_mov_b32 m0, s43
	ds_read_b128 v[152:155], v184 offset:16384
	ds_read_b128 v[156:159], v184 offset:17408
	ds_read_b128 v[162:165], v184 offset:18432
	ds_read_b128 v[172:175], v184 offset:19456
	ds_read_b128 v[176:179], v184 offset:20480
	ds_read_b128 v[196:199], v184 offset:21504
	ds_read_b128 v[200:203], v184 offset:22528
	ds_read_b128 v[204:207], v184 offset:23552
	global_load_lds_dwordx4 v160, s[34:35]
	s_mov_b32 m0, s50
	s_add_u32 vcc_lo, s34, s88
	s_addc_u32 vcc_hi, s35, s89
	global_load_lds_dwordx4 v160, vcc
	s_barrier
; #define G_STAGE(bufoff, gbase, o0, h64) do { \
;         __builtin_amdgcn_global_load_lds((const unsigned*)((const char*)(gbase) + (o0)), (LAS unsigned*)(lds + (bufoff) + ldsw), 16, 0, 0); \
;         __builtin_amdgcn_global_load_lds((const unsigned*)((const char*)(gbase) + (h64) + (o0)), (LAS unsigned*)(lds + (bufoff) + ldsw + 8192), 16, 0, 0); } while (0)
; #define G_LDA(dst, b, h) do { _Pragma("unroll") for (int m = 0; m < 4; ++m) _Pragma("unroll") for (int k = 0; k < 2; ++k) dst[m][k] = *(const LAS bf16x8*)(lds + G_SA(b, h) + aoff + m * 2048 + k * 1024); } while (0)
; #define G_LDB(dst, b, h) do { _Pragma("unroll") for (int n = 0; n < 2; ++n) _Pragma("unroll") for (int k = 0; k < 2; ++k) dst[n][k] = *(const LAS bf16x8*)(lds + G_SB(b, h) + boff + n * 2048 + k * 1024); } while (0)
; #define G_WAIT_V(n) asm volatile("s_waitcnt vmcnt(" #n ")" ::: "memory")
; #define G_BAR __builtin_amdgcn_s_barrier()
;     ...
;         for (int t = 0; t < nt; t += 2) {
;             const bool last = (t == nt - 2);
;             const char* a1 = cA + (size_t)(t + 1) * ckA;
;             const char* a2 = last ? nA : cA + (size_t)(t + 2) * ckA; const char* b2 = last ? nB : cB + (size_t)(t + 2) * kB;
;             const char* a3 = a2 + ckA; const char* b3 = b2 + kB;
;             G_LDB(B0, 0, 0); G_SCHED; G_LDA(At, 0, 0); G_STAGE(G_SA(1, 1), a1 + chA, cA0, qA);
;             G_WAIT_L(8); G_BAR; G_WAIT_L(0); G_MMA(0, 0, At, B0); G_BAR; G_SCHED;
;             G_LDB(B1, 0, 1); G_STAGE(G_SB(0, 0), b2, cB0, qB);
;             G_BAR; G_WAIT_L(0); G_MMA(0, 1, At, B1); G_BAR;
;             G_LDA(At, 0, 1); G_STAGE(G_SA(0, 0), a2, cA0, qA);
;             G_BAR; G_WAIT_L(0); G_MMA(1, 0, At, B0); G_BAR; G_SCHED;
;             G_STAGE(G_SB(0, 1), b2 + chB, cB0, qB);
;             G_WAIT_V(6); G_BAR; G_MMA(1, 1, At, B1); G_BAR;
;             G_LDB(B0, 1, 0); G_SCHED; G_LDA(At, 1, 0); G_STAGE(G_SA(0, 1), a2 + chA, cA0, qA);
;             G_WAIT_L(8); G_BAR; G_WAIT_L(0); G_MMA(0, 0, At, B0); G_BAR; G_SCHED;
;             G_LDB(B1, 1, 1); G_STAGE(G_SB(1, 0), b3, cB0, qB);
;             G_BAR; G_WAIT_L(0); G_MMA(0, 1, At, B1); G_BAR;
;             G_LDA(At, 1, 1); G_STAGE(G_SA(1, 0), a3, cA0, qA);
;             G_BAR; G_WAIT_L(0); G_MMA(1, 0, At, B0); G_BAR; G_SCHED;
;             G_STAGE(G_SB(1, 1), b3 + chB, cB0, qB);
;             G_WAIT_V(6); G_BAR; G_MMA(1, 1, At, B1); G_BAR;
	s_waitcnt lgkmcnt(0)
	v_mfma_f32_16x16x32_bf16 v[76:79], v[56:59], v[152:155], 0
	v_mfma_f32_16x16x32_bf16 v[72:75], v[144:147], v[152:155], 0
	v_mfma_f32_16x16x32_bf16 v[52:55], v[56:59], v[162:165], 0
	v_mfma_f32_16x16x32_bf16 v[48:51], v[144:147], v[162:165], 0
	v_mfma_f32_16x16x32_bf16 v[36:39], v[56:59], v[176:179], 0
	v_mfma_f32_16x16x32_bf16 v[32:35], v[144:147], v[176:179], 0
	v_mfma_f32_16x16x32_bf16 v[20:23], v[56:59], v[200:203], 0
	v_mfma_f32_16x16x32_bf16 v[16:19], v[144:147], v[200:203], 0
	v_mfma_f32_16x16x32_bf16 v[76:79], v[60:63], v[156:159], v[76:79]
	v_mfma_f32_16x16x32_bf16 v[72:75], v[148:151], v[156:159], v[72:75]
	v_mfma_f32_16x16x32_bf16 v[52:55], v[60:63], v[172:175], v[52:55]
	v_mfma_f32_16x16x32_bf16 v[48:51], v[148:151], v[172:175], v[48:51]
	v_mfma_f32_16x16x32_bf16 v[36:39], v[60:63], v[196:199], v[36:39]
	v_mfma_f32_16x16x32_bf16 v[32:35], v[148:151], v[196:199], v[32:35]
	v_mfma_f32_16x16x32_bf16 v[20:23], v[60:63], v[204:207], v[20:23]
	v_mfma_f32_16x16x32_bf16 v[16:19], v[148:151], v[204:207], v[16:19]
	s_barrier
	s_mov_b32 m0, s63
	s_add_u32 vcc_lo, s26, s82
	s_addc_u32 vcc_hi, s27, s83
	global_load_lds_dwordx4 v2, vcc
	s_mov_b32 m0, s62
	s_add_u32 vcc_lo, s26, s94
	s_addc_u32 vcc_hi, s27, s95
	global_load_lds_dwordx4 v2, vcc
	s_waitcnt vmcnt(6)
	s_barrier
	v_mfma_f32_16x16x32_bf16 v[44:47], v[208:211], v[162:165], 0
	v_mfma_f32_16x16x32_bf16 v[40:43], v[216:219], v[162:165], 0
	v_mfma_f32_16x16x32_bf16 v[28:31], v[208:211], v[176:179], 0
	v_mfma_f32_16x16x32_bf16 v[24:27], v[216:219], v[176:179], 0
	v_mfma_f32_16x16x32_bf16 v[12:15], v[208:211], v[200:203], 0
	v_mfma_f32_16x16x32_bf16 v[8:11], v[216:219], v[200:203], 0
	v_mfma_f32_16x16x32_bf16 v[56:59], v[208:211], v[152:155], 0
	v_mfma_f32_16x16x32_bf16 v[60:63], v[216:219], v[152:155], 0
	v_mfma_f32_16x16x32_bf16 v[44:47], v[212:215], v[172:175], v[44:47]
	v_mfma_f32_16x16x32_bf16 v[40:43], v[220:223], v[172:175], v[40:43]
	v_mfma_f32_16x16x32_bf16 v[28:31], v[212:215], v[196:199], v[28:31]
	v_mfma_f32_16x16x32_bf16 v[24:27], v[220:223], v[196:199], v[24:27]
	v_mfma_f32_16x16x32_bf16 v[12:15], v[212:215], v[204:207], v[12:15]
	v_mfma_f32_16x16x32_bf16 v[8:11], v[220:223], v[204:207], v[8:11]
	v_mfma_f32_16x16x32_bf16 v[56:59], v[212:215], v[156:159], v[56:59]
	v_mfma_f32_16x16x32_bf16 v[60:63], v[220:223], v[156:159], v[60:63]
	s_barrier
	ds_read_b128 v[64:67], v255 offset:32768
	ds_read_b128 v[68:71], v255 offset:33792
	ds_read_b128 v[144:147], v255 offset:34816
	ds_read_b128 v[148:151], v255 offset:35840
	s_mov_b32 m0, s51
	ds_read_b128 v[152:155], v184 offset:32768
	ds_read_b128 v[156:159], v184 offset:33792
	ds_read_b128 v[162:165], v184 offset:34816
	ds_read_b128 v[172:175], v184 offset:35840
	ds_read_b128 v[176:179], v184 offset:36864
	ds_read_b128 v[196:199], v184 offset:37888
	ds_read_b128 v[200:203], v184 offset:38912
	ds_read_b128 v[204:207], v184 offset:39936
	s_add_u32 vcc_lo, s34, s86
	s_addc_u32 vcc_hi, s35, s87
	global_load_lds_dwordx4 v160, vcc
	s_mov_b32 m0, s52
	s_add_u32 vcc_lo, s34, s96
	s_addc_u32 vcc_hi, s35, s97
	global_load_lds_dwordx4 v160, vcc
	s_waitcnt lgkmcnt(8)
	s_barrier
	s_waitcnt lgkmcnt(0)
	v_mfma_f32_16x16x32_bf16 v[140:143], v[64:67], v[152:155], v[140:143]
	v_mfma_f32_16x16x32_bf16 v[136:139], v[144:147], v[152:155], v[136:139]
	v_mfma_f32_16x16x32_bf16 v[124:127], v[64:67], v[162:165], v[124:127]
	v_mfma_f32_16x16x32_bf16 v[120:123], v[144:147], v[162:165], v[120:123]
	v_mfma_f32_16x16x32_bf16 v[108:111], v[64:67], v[176:179], v[108:111]
	v_mfma_f32_16x16x32_bf16 v[104:107], v[144:147], v[176:179], v[104:107]
	v_mfma_f32_16x16x32_bf16 v[92:95], v[64:67], v[200:203], v[92:95]
	v_mfma_f32_16x16x32_bf16 v[88:91], v[144:147], v[200:203], v[88:91]
	v_mfma_f32_16x16x32_bf16 v[140:143], v[68:71], v[156:159], v[140:143]
	v_mfma_f32_16x16x32_bf16 v[136:139], v[148:151], v[156:159], v[136:139]
	v_mfma_f32_16x16x32_bf16 v[124:127], v[68:71], v[172:175], v[124:127]
	v_mfma_f32_16x16x32_bf16 v[120:123], v[148:151], v[172:175], v[120:123]
	v_mfma_f32_16x16x32_bf16 v[108:111], v[68:71], v[196:199], v[108:111]
	v_mfma_f32_16x16x32_bf16 v[104:107], v[148:151], v[196:199], v[104:107]
	v_mfma_f32_16x16x32_bf16 v[92:95], v[68:71], v[204:207], v[92:95]
	v_mfma_f32_16x16x32_bf16 v[88:91], v[148:151], v[204:207], v[88:91]
	s_barrier
	s_mov_b32 m0, s30
	ds_read_b128 v[208:211], v255 offset:49152
	ds_read_b128 v[212:215], v255 offset:50176
	ds_read_b128 v[216:219], v255 offset:51200
	ds_read_b128 v[220:223], v255 offset:52224
	s_add_u32 vcc_lo, s26, s46
	s_addc_u32 vcc_hi, s27, s47
	global_load_lds_dwordx4 v2, vcc
	s_mov_b32 m0, s67
	s_add_u32 vcc_lo, s26, s70
	s_addc_u32 vcc_hi, s27, s71
	global_load_lds_dwordx4 v2, vcc
	s_barrier
	s_waitcnt lgkmcnt(0)
	v_mfma_f32_16x16x32_bf16 v[132:135], v[208:211], v[152:155], v[132:135]
	v_mfma_f32_16x16x32_bf16 v[128:131], v[216:219], v[152:155], v[128:131]
	v_mfma_f32_16x16x32_bf16 v[116:119], v[208:211], v[162:165], v[116:119]
	v_mfma_f32_16x16x32_bf16 v[112:115], v[216:219], v[162:165], v[112:115]
	v_mfma_f32_16x16x32_bf16 v[100:103], v[208:211], v[176:179], v[100:103]
	v_mfma_f32_16x16x32_bf16 v[96:99], v[216:219], v[176:179], v[96:99]
	v_mfma_f32_16x16x32_bf16 v[84:87], v[208:211], v[200:203], v[84:87]
	v_mfma_f32_16x16x32_bf16 v[80:83], v[216:219], v[200:203], v[80:83]
	v_mfma_f32_16x16x32_bf16 v[132:135], v[212:215], v[156:159], v[132:135]
	v_mfma_f32_16x16x32_bf16 v[128:131], v[220:223], v[156:159], v[128:131]
	v_mfma_f32_16x16x32_bf16 v[116:119], v[212:215], v[172:175], v[116:119]
	v_mfma_f32_16x16x32_bf16 v[112:115], v[220:223], v[172:175], v[112:115]
	v_mfma_f32_16x16x32_bf16 v[100:103], v[212:215], v[196:199], v[100:103]
	v_mfma_f32_16x16x32_bf16 v[96:99], v[220:223], v[196:199], v[96:99]
	v_mfma_f32_16x16x32_bf16 v[84:87], v[212:215], v[204:207], v[84:87]
	v_mfma_f32_16x16x32_bf16 v[80:83], v[220:223], v[204:207], v[80:83]
	s_barrier
; #define G_STAGE(bufoff, gbase, o0, h64) do { \
;         __builtin_amdgcn_global_load_lds((const unsigned*)((const char*)(gbase) + (o0)), (LAS unsigned*)(lds + (bufoff) + ldsw), 16, 0, 0); \
;         __builtin_amdgcn_global_load_lds((const unsigned*)((const char*)(gbase) + (h64) + (o0)), (LAS unsigned*)(lds + (bufoff) + ldsw + 8192), 16, 0, 0); } while (0)
; #define G_LDA(dst, b, h) do { _Pragma("unroll") for (int m = 0; m < 4; ++m) _Pragma("unroll") for (int k = 0; k < 2; ++k) dst[m][k] = *(const LAS bf16x8*)(lds + G_SA(b, h) + aoff + m * 2048 + k * 1024); } while (0)
; #define G_LDB(dst, b, h) do { _Pragma("unroll") for (int n = 0; n < 2; ++n) _Pragma("unroll") for (int k = 0; k < 2; ++k) dst[n][k] = *(const LAS bf16x8*)(lds + G_SB(b, h) + boff + n * 2048 + k * 1024); } while (0)
; #define G_WAIT_V(n) asm volatile("s_waitcnt vmcnt(" #n ")" ::: "memory")
; #define G_BAR __builtin_amdgcn_s_barrier()
;     ...
;         for (int t = 0; t < nt; t += 2) {
;             const bool last = (t == nt - 2);
;             const char* a1 = cA + (size_t)(t + 1) * ckA;
;             const char* a2 = last ? nA : cA + (size_t)(t + 2) * ckA; const char* b2 = last ? nB : cB + (size_t)(t + 2) * kB;
;             const char* a3 = a2 + ckA; const char* b3 = b2 + kB;
;             G_LDB(B0, 0, 0); G_SCHED; G_LDA(At, 0, 0); G_STAGE(G_SA(1, 1), a1 + chA, cA0, qA);
;             G_WAIT_L(8); G_BAR; G_WAIT_L(0); G_MMA(0, 0, At, B0); G_BAR; G_SCHED;
;             G_LDB(B1, 0, 1); G_STAGE(G_SB(0, 0), b2, cB0, qB);
;             G_BAR; G_WAIT_L(0); G_MMA(0, 1, At, B1); G_BAR;
;             G_LDA(At, 0, 1); G_STAGE(G_SA(0, 0), a2, cA0, qA);
;             G_BAR; G_WAIT_L(0); G_MMA(1, 0, At, B0); G_BAR; G_SCHED;
;             G_STAGE(G_SB(0, 1), b2 + chB, cB0, qB);
;             G_WAIT_V(6); G_BAR; G_MMA(1, 1, At, B1); G_BAR;
;             G_LDB(B0, 1, 0); G_SCHED; G_LDA(At, 1, 0); G_STAGE(G_SA(0, 1), a2 + chA, cA0, qA);
;             G_WAIT_L(8); G_BAR; G_WAIT_L(0); G_MMA(0, 0, At, B0); G_BAR; G_SCHED;
;             G_LDB(B1, 1, 1); G_STAGE(G_SB(1, 0), b3, cB0, qB);
;             G_BAR; G_WAIT_L(0); G_MMA(0, 1, At, B1); G_BAR;
;             G_LDA(At, 1, 1); G_STAGE(G_SA(1, 0), a3, cA0, qA);
;             G_BAR; G_WAIT_L(0); G_MMA(1, 0, At, B0); G_BAR; G_SCHED;
;             G_STAGE(G_SB(1, 1), b3 + chB, cB0, qB);
;             G_WAIT_V(6); G_BAR; G_MMA(1, 1, At, B1); G_BAR;
	s_mov_b32 m0, s53
	ds_read_b128 v[152:155], v184 offset:49152
	ds_read_b128 v[156:159], v184 offset:50176
	ds_read_b128 v[162:165], v184 offset:51200
	ds_read_b128 v[172:175], v184 offset:52224
	ds_read_b128 v[176:179], v184 offset:53248
	ds_read_b128 v[196:199], v184 offset:54272
	ds_read_b128 v[200:203], v184 offset:55296
	ds_read_b128 v[204:207], v184 offset:56320
	s_add_u32 vcc_lo, s34, s46
	s_addc_u32 vcc_hi, s35, s47
	global_load_lds_dwordx4 v160, vcc
	s_mov_b32 m0, s54
	s_add_u32 vcc_lo, s34, s68
	s_addc_u32 vcc_hi, s35, s69
	global_load_lds_dwordx4 v160, vcc
	s_barrier
	s_waitcnt lgkmcnt(0)
	v_mfma_f32_16x16x32_bf16 v[76:79], v[64:67], v[152:155], v[76:79]
	v_mfma_f32_16x16x32_bf16 v[72:75], v[144:147], v[152:155], v[72:75]
	v_mfma_f32_16x16x32_bf16 v[52:55], v[64:67], v[162:165], v[52:55]
	v_mfma_f32_16x16x32_bf16 v[48:51], v[144:147], v[162:165], v[48:51]
	v_mfma_f32_16x16x32_bf16 v[36:39], v[64:67], v[176:179], v[36:39]
	v_mfma_f32_16x16x32_bf16 v[32:35], v[144:147], v[176:179], v[32:35]
	v_mfma_f32_16x16x32_bf16 v[20:23], v[64:67], v[200:203], v[20:23]
	v_mfma_f32_16x16x32_bf16 v[16:19], v[144:147], v[200:203], v[16:19]
	v_mfma_f32_16x16x32_bf16 v[76:79], v[68:71], v[156:159], v[76:79]
	v_mfma_f32_16x16x32_bf16 v[72:75], v[148:151], v[156:159], v[72:75]
	v_mfma_f32_16x16x32_bf16 v[52:55], v[68:71], v[172:175], v[52:55]
	v_mfma_f32_16x16x32_bf16 v[48:51], v[148:151], v[172:175], v[48:51]
	v_mfma_f32_16x16x32_bf16 v[36:39], v[68:71], v[196:199], v[36:39]
	v_mfma_f32_16x16x32_bf16 v[32:35], v[148:151], v[196:199], v[32:35]
	v_mfma_f32_16x16x32_bf16 v[20:23], v[68:71], v[204:207], v[20:23]
	v_mfma_f32_16x16x32_bf16 v[16:19], v[148:151], v[204:207], v[16:19]
	s_barrier
	s_mov_b32 m0, s65
	s_add_u32 vcc_lo, s26, s84
	s_addc_u32 vcc_hi, s27, s85
	global_load_lds_dwordx4 v2, vcc
	s_mov_b32 m0, s64
	s_add_u32 vcc_lo, s26, s28
	s_addc_u32 vcc_hi, s27, s29
	global_load_lds_dwordx4 v2, vcc
	s_waitcnt vmcnt(6)
	s_barrier
	v_mfma_f32_16x16x32_bf16 v[56:59], v[208:211], v[152:155], v[56:59]
	v_mfma_f32_16x16x32_bf16 v[68:71], v[212:215], v[156:159], v[56:59]
	v_mfma_f32_16x16x32_bf16 v[56:59], v[216:219], v[152:155], v[60:63]
	v_mfma_f32_16x16x32_bf16 v[44:47], v[208:211], v[162:165], v[44:47]
	v_mfma_f32_16x16x32_bf16 v[40:43], v[216:219], v[162:165], v[40:43]
	v_mfma_f32_16x16x32_bf16 v[28:31], v[208:211], v[176:179], v[28:31]
	v_mfma_f32_16x16x32_bf16 v[24:27], v[216:219], v[176:179], v[24:27]
	v_mfma_f32_16x16x32_bf16 v[12:15], v[208:211], v[200:203], v[12:15]
	v_mfma_f32_16x16x32_bf16 v[8:11], v[216:219], v[200:203], v[8:11]
	v_mfma_f32_16x16x32_bf16 v[64:67], v[220:223], v[156:159], v[56:59]
	v_mfma_f32_16x16x32_bf16 v[44:47], v[212:215], v[172:175], v[44:47]
	v_mfma_f32_16x16x32_bf16 v[40:43], v[220:223], v[172:175], v[40:43]
	v_mfma_f32_16x16x32_bf16 v[28:31], v[212:215], v[196:199], v[28:31]
	v_mfma_f32_16x16x32_bf16 v[24:27], v[220:223], v[196:199], v[24:27]
	v_mfma_f32_16x16x32_bf16 v[12:15], v[212:215], v[204:207], v[12:15]
	v_mfma_f32_16x16x32_bf16 v[8:11], v[220:223], v[204:207], v[8:11]
	s_andn2_b64 vcc, exec, s[24:25]
	s_mov_b64 s[26:27], -1
	s_mov_b64 s[24:25], 0
	s_mov_b64 s[30:31], 0x100
	s_cbranch_vccz .Ldb_SSM2_cont
	s_branch .Ldb_SSM2_xl
.LBB0_742:
	s_add_u32 s36, s2, s30
	s_addc_u32 s37, s3, s31
	s_add_u32 s19, s36, 0x100
	s_addc_u32 s35, s37, 0
	s_and_b64 s[4:5], s[26:27], exec
	s_cselect_b32 s34, s12, s19
	s_cselect_b32 s35, s13, s35
	s_add_u32 s4, s20, s30
	s_addc_u32 s5, s21, s31
	s_add_u32 s19, s4, 0x100
	s_addc_u32 s30, s5, 0
	s_add_i32 s44, 0, 0x10000
	ds_read_b128 v[56:59], v255 offset:0
	ds_read_b128 v[60:63], v255 offset:1024
	ds_read_b128 v[144:147], v255 offset:2048
	ds_read_b128 v[148:151], v255 offset:3072
	s_and_b64 s[4:5], s[26:27], exec
	s_cselect_b32 s26, s16, s19
	s_cselect_b32 s27, s17, s30
	s_add_i32 s48, 0, 0x14000
	s_add_i32 s31, 0, 0x18000
	s_add_i32 s19, 0, 0x1c000
	s_add_i32 s49, s44, s38
	s_add_i32 s63, s48, s38
	s_add_i32 s30, s31, s38
	s_add_i32 s65, s19, s38
	s_add_i32 m0, s43, 0xc000
	s_add_i32 s45, s43, 0xe000
	s_add_i32 s66, s49, 0x2000
	s_add_i32 s62, s63, 0x2000
	s_add_i32 s67, s30, 0x2000
	s_add_i32 s64, s65, 0x2000
	s_mov_b64 s[4:5], 0x200080
	s_add_u32 vcc_lo, s36, s4
	s_addc_u32 vcc_hi, s37, s5
	s_mov_b64 s[4:5], 0x300080
	ds_read_b128 v[152:155], v184
	ds_read_b128 v[156:159], v184 offset:1024
	ds_read_b128 v[162:165], v184 offset:2048
	ds_read_b128 v[172:175], v184 offset:3072
	ds_read_b128 v[176:179], v184 offset:4096
	ds_read_b128 v[196:199], v184 offset:5120
	ds_read_b128 v[200:203], v184 offset:6144
	ds_read_b128 v[204:207], v184 offset:7168
	global_load_lds_dwordx4 v160, vcc
	s_mov_b32 m0, s45
	s_add_u32 vcc_lo, s36, s4
	s_addc_u32 vcc_hi, s37, s5
	global_load_lds_dwordx4 v160, vcc
	s_waitcnt lgkmcnt(8)
	s_barrier
	s_waitcnt lgkmcnt(0)
	v_mfma_f32_16x16x32_bf16 v[140:143], v[56:59], v[152:155], v[140:143]
	v_mfma_f32_16x16x32_bf16 v[136:139], v[144:147], v[152:155], v[136:139]
	v_mfma_f32_16x16x32_bf16 v[124:127], v[56:59], v[162:165], v[124:127]
	v_mfma_f32_16x16x32_bf16 v[120:123], v[144:147], v[162:165], v[120:123]
	v_mfma_f32_16x16x32_bf16 v[108:111], v[56:59], v[176:179], v[108:111]
	v_mfma_f32_16x16x32_bf16 v[104:107], v[144:147], v[176:179], v[104:107]
	v_mfma_f32_16x16x32_bf16 v[92:95], v[56:59], v[200:203], v[92:95]
	v_mfma_f32_16x16x32_bf16 v[88:91], v[144:147], v[200:203], v[88:91]
	v_mfma_f32_16x16x32_bf16 v[140:143], v[60:63], v[156:159], v[140:143]
	v_mfma_f32_16x16x32_bf16 v[136:139], v[148:151], v[156:159], v[136:139]
	v_mfma_f32_16x16x32_bf16 v[124:127], v[60:63], v[172:175], v[124:127]
	v_mfma_f32_16x16x32_bf16 v[120:123], v[148:151], v[172:175], v[120:123]
	v_mfma_f32_16x16x32_bf16 v[108:111], v[60:63], v[196:199], v[108:111]
	v_mfma_f32_16x16x32_bf16 v[104:107], v[148:151], v[196:199], v[104:107]
	v_mfma_f32_16x16x32_bf16 v[92:95], v[60:63], v[204:207], v[92:95]
	v_mfma_f32_16x16x32_bf16 v[88:91], v[148:151], v[204:207], v[88:91]
	s_barrier
; #define G_STAGE(bufoff, gbase, o0, h64) do { \
;         __builtin_amdgcn_global_load_lds((const unsigned*)((const char*)(gbase) + (o0)), (LAS unsigned*)(lds + (bufoff) + ldsw), 16, 0, 0); \
;         __builtin_amdgcn_global_load_lds((const unsigned*)((const char*)(gbase) + (h64) + (o0)), (LAS unsigned*)(lds + (bufoff) + ldsw + 8192), 16, 0, 0); } while (0)
; #define G_LDA(dst, b, h) do { _Pragma("unroll") for (int m = 0; m < 4; ++m) _Pragma("unroll") for (int k = 0; k < 2; ++k) dst[m][k] = *(const LAS bf16x8*)(lds + G_SA(b, h) + aoff + m * 2048 + k * 1024); } while (0)
; #define G_LDB(dst, b, h) do { _Pragma("unroll") for (int n = 0; n < 2; ++n) _Pragma("unroll") for (int k = 0; k < 2; ++k) dst[n][k] = *(const LAS bf16x8*)(lds + G_SB(b, h) + boff + n * 2048 + k * 1024); } while (0)
; #define G_WAIT_V(n) asm volatile("s_waitcnt vmcnt(" #n ")" ::: "memory")
; #define G_BAR __builtin_amdgcn_s_barrier()
;     ...
;         for (int t = 0; t < nt; t += 2) {
;             const bool last = (t == nt - 2);
;             const char* a1 = cA + (size_t)(t + 1) * ckA;
;             const char* a2 = last ? nA : cA + (size_t)(t + 2) * ckA; const char* b2 = last ? nB : cB + (size_t)(t + 2) * kB;
;             const char* a3 = a2 + ckA; const char* b3 = b2 + kB;
;             G_LDB(B0, 0, 0); G_SCHED; G_LDA(At, 0, 0); G_STAGE(G_SA(1, 1), a1 + chA, cA0, qA);
;             G_WAIT_L(8); G_BAR; G_WAIT_L(0); G_MMA(0, 0, At, B0); G_BAR; G_SCHED;
;             G_LDB(B1, 0, 1); G_STAGE(G_SB(0, 0), b2, cB0, qB);
;             G_BAR; G_WAIT_L(0); G_MMA(0, 1, At, B1); G_BAR;
;             G_LDA(At, 0, 1); G_STAGE(G_SA(0, 0), a2, cA0, qA);
;             G_BAR; G_WAIT_L(0); G_MMA(1, 0, At, B0); G_BAR; G_SCHED;
;             G_STAGE(G_SB(0, 1), b2 + chB, cB0, qB);
;             G_WAIT_V(6); G_BAR; G_MMA(1, 1, At, B1); G_BAR;
;             G_LDB(B0, 1, 0); G_SCHED; G_LDA(At, 1, 0); G_STAGE(G_SA(0, 1), a2 + chA, cA0, qA);
;             G_WAIT_L(8); G_BAR; G_WAIT_L(0); G_MMA(0, 0, At, B0); G_BAR; G_SCHED;
;             G_LDB(B1, 1, 1); G_STAGE(G_SB(1, 0), b3, cB0, qB);
;             G_BAR; G_WAIT_L(0); G_MMA(0, 1, At, B1); G_BAR;
;             G_LDA(At, 1, 1); G_STAGE(G_SA(1, 0), a3, cA0, qA);
;             G_BAR; G_WAIT_L(0); G_MMA(1, 0, At, B0); G_BAR; G_SCHED;
;             G_STAGE(G_SB(1, 1), b3 + chB, cB0, qB);
;             G_WAIT_V(6); G_BAR; G_MMA(1, 1, At, B1); G_BAR;
	s_mov_b32 m0, s49
	ds_read_b128 v[208:211], v255 offset:16384
	ds_read_b128 v[212:215], v255 offset:17408
	ds_read_b128 v[216:219], v255 offset:18432
	ds_read_b128 v[220:223], v255 offset:19456
	global_load_lds_dwordx4 v2, s[26:27]
	s_mov_b32 m0, s66
	s_add_u32 vcc_lo, s26, s92
	s_addc_u32 vcc_hi, s27, s93
	global_load_lds_dwordx4 v2, vcc
	s_barrier
	s_waitcnt lgkmcnt(0)
	v_mfma_f32_16x16x32_bf16 v[132:135], v[208:211], v[152:155], v[132:135]
	v_mfma_f32_16x16x32_bf16 v[128:131], v[216:219], v[152:155], v[128:131]
	v_mfma_f32_16x16x32_bf16 v[116:119], v[208:211], v[162:165], v[116:119]
	v_mfma_f32_16x16x32_bf16 v[112:115], v[216:219], v[162:165], v[112:115]
	v_mfma_f32_16x16x32_bf16 v[100:103], v[208:211], v[176:179], v[100:103]
	v_mfma_f32_16x16x32_bf16 v[96:99], v[216:219], v[176:179], v[96:99]
	v_mfma_f32_16x16x32_bf16 v[84:87], v[208:211], v[200:203], v[84:87]
	v_mfma_f32_16x16x32_bf16 v[80:83], v[216:219], v[200:203], v[80:83]
	v_mfma_f32_16x16x32_bf16 v[132:135], v[212:215], v[156:159], v[132:135]
	v_mfma_f32_16x16x32_bf16 v[128:131], v[220:223], v[156:159], v[128:131]
	v_mfma_f32_16x16x32_bf16 v[116:119], v[212:215], v[172:175], v[116:119]
	v_mfma_f32_16x16x32_bf16 v[112:115], v[220:223], v[172:175], v[112:115]
	v_mfma_f32_16x16x32_bf16 v[100:103], v[212:215], v[196:199], v[100:103]
	v_mfma_f32_16x16x32_bf16 v[96:99], v[220:223], v[196:199], v[96:99]
	v_mfma_f32_16x16x32_bf16 v[84:87], v[212:215], v[204:207], v[84:87]
	v_mfma_f32_16x16x32_bf16 v[80:83], v[220:223], v[204:207], v[80:83]
	s_barrier
	s_mov_b32 m0, s43
	ds_read_b128 v[152:155], v184 offset:16384
	ds_read_b128 v[156:159], v184 offset:17408
	ds_read_b128 v[162:165], v184 offset:18432
	ds_read_b128 v[172:175], v184 offset:19456
	ds_read_b128 v[176:179], v184 offset:20480
	ds_read_b128 v[196:199], v184 offset:21504
	ds_read_b128 v[200:203], v184 offset:22528
	ds_read_b128 v[204:207], v184 offset:23552
	global_load_lds_dwordx4 v160, s[34:35]
	s_mov_b32 m0, s50
	s_add_u32 vcc_lo, s34, s88
	s_addc_u32 vcc_hi, s35, s89
	global_load_lds_dwordx4 v160, vcc
	s_barrier
	s_waitcnt lgkmcnt(0)
	v_mfma_f32_16x16x32_bf16 v[76:79], v[56:59], v[152:155], v[76:79]
	v_mfma_f32_16x16x32_bf16 v[72:75], v[144:147], v[152:155], v[72:75]
	v_mfma_f32_16x16x32_bf16 v[52:55], v[56:59], v[162:165], v[52:55]
	v_mfma_f32_16x16x32_bf16 v[48:51], v[144:147], v[162:165], v[48:51]
	v_mfma_f32_16x16x32_bf16 v[36:39], v[56:59], v[176:179], v[36:39]
	v_mfma_f32_16x16x32_bf16 v[32:35], v[144:147], v[176:179], v[32:35]
	v_mfma_f32_16x16x32_bf16 v[20:23], v[56:59], v[200:203], v[20:23]
	v_mfma_f32_16x16x32_bf16 v[16:19], v[144:147], v[200:203], v[16:19]
	v_mfma_f32_16x16x32_bf16 v[76:79], v[60:63], v[156:159], v[76:79]
	v_mfma_f32_16x16x32_bf16 v[72:75], v[148:151], v[156:159], v[72:75]
	v_mfma_f32_16x16x32_bf16 v[52:55], v[60:63], v[172:175], v[52:55]
	v_mfma_f32_16x16x32_bf16 v[48:51], v[148:151], v[172:175], v[48:51]
	v_mfma_f32_16x16x32_bf16 v[36:39], v[60:63], v[196:199], v[36:39]
	v_mfma_f32_16x16x32_bf16 v[32:35], v[148:151], v[196:199], v[32:35]
	v_mfma_f32_16x16x32_bf16 v[20:23], v[60:63], v[204:207], v[20:23]
	v_mfma_f32_16x16x32_bf16 v[16:19], v[148:151], v[204:207], v[16:19]
	s_barrier
	s_mov_b32 m0, s63
	s_add_u32 vcc_lo, s26, s82
	s_addc_u32 vcc_hi, s27, s83
	global_load_lds_dwordx4 v2, vcc
	s_mov_b32 m0, s62
	s_add_u32 vcc_lo, s26, s94
	s_addc_u32 vcc_hi, s27, s95
	global_load_lds_dwordx4 v2, vcc
	s_waitcnt vmcnt(6)
	s_barrier
	v_mfma_f32_16x16x32_bf16 v[44:47], v[208:211], v[162:165], v[44:47]
	v_mfma_f32_16x16x32_bf16 v[40:43], v[216:219], v[162:165], v[40:43]
	v_mfma_f32_16x16x32_bf16 v[28:31], v[208:211], v[176:179], v[28:31]
	v_mfma_f32_16x16x32_bf16 v[24:27], v[216:219], v[176:179], v[24:27]
	v_mfma_f32_16x16x32_bf16 v[12:15], v[208:211], v[200:203], v[12:15]
	v_mfma_f32_16x16x32_bf16 v[8:11], v[216:219], v[200:203], v[8:11]
	v_mfma_f32_16x16x32_bf16 v[56:59], v[208:211], v[152:155], v[68:71]
	v_mfma_f32_16x16x32_bf16 v[60:63], v[216:219], v[152:155], v[64:67]
	v_mfma_f32_16x16x32_bf16 v[44:47], v[212:215], v[172:175], v[44:47]
	v_mfma_f32_16x16x32_bf16 v[40:43], v[220:223], v[172:175], v[40:43]
	v_mfma_f32_16x16x32_bf16 v[28:31], v[212:215], v[196:199], v[28:31]
	v_mfma_f32_16x16x32_bf16 v[24:27], v[220:223], v[196:199], v[24:27]
	v_mfma_f32_16x16x32_bf16 v[12:15], v[212:215], v[204:207], v[12:15]
	v_mfma_f32_16x16x32_bf16 v[8:11], v[220:223], v[204:207], v[8:11]
	v_mfma_f32_16x16x32_bf16 v[56:59], v[212:215], v[156:159], v[56:59]
	v_mfma_f32_16x16x32_bf16 v[60:63], v[220:223], v[156:159], v[60:63]
	s_barrier
	ds_read_b128 v[64:67], v255 offset:32768
	ds_read_b128 v[68:71], v255 offset:33792
	ds_read_b128 v[144:147], v255 offset:34816
	ds_read_b128 v[148:151], v255 offset:35840
	s_mov_b32 m0, s51
	ds_read_b128 v[152:155], v184 offset:32768
	ds_read_b128 v[156:159], v184 offset:33792
	ds_read_b128 v[162:165], v184 offset:34816
	ds_read_b128 v[172:175], v184 offset:35840
	ds_read_b128 v[176:179], v184 offset:36864
	ds_read_b128 v[196:199], v184 offset:37888
	ds_read_b128 v[200:203], v184 offset:38912
	ds_read_b128 v[204:207], v184 offset:39936
	s_add_u32 vcc_lo, s34, s86
	s_addc_u32 vcc_hi, s35, s87
	global_load_lds_dwordx4 v160, vcc
	s_mov_b32 m0, s52
	s_add_u32 vcc_lo, s34, s96
	s_addc_u32 vcc_hi, s35, s97
	global_load_lds_dwordx4 v160, vcc
	s_waitcnt lgkmcnt(8)
	s_barrier
; #define G_STAGE(bufoff, gbase, o0, h64) do { \
;         __builtin_amdgcn_global_load_lds((const unsigned*)((const char*)(gbase) + (o0)), (LAS unsigned*)(lds + (bufoff) + ldsw), 16, 0, 0); \
;         __builtin_amdgcn_global_load_lds((const unsigned*)((const char*)(gbase) + (h64) + (o0)), (LAS unsigned*)(lds + (bufoff) + ldsw + 8192), 16, 0, 0); } while (0)
; #define G_LDA(dst, b, h) do { _Pragma("unroll") for (int m = 0; m < 4; ++m) _Pragma("unroll") for (int k = 0; k < 2; ++k) dst[m][k] = *(const LAS bf16x8*)(lds + G_SA(b, h) + aoff + m * 2048 + k * 1024); } while (0)
; #define G_LDB(dst, b, h) do { _Pragma("unroll") for (int n = 0; n < 2; ++n) _Pragma("unroll") for (int k = 0; k < 2; ++k) dst[n][k] = *(const LAS bf16x8*)(lds + G_SB(b, h) + boff + n * 2048 + k * 1024); } while (0)
; #define G_WAIT_V(n) asm volatile("s_waitcnt vmcnt(" #n ")" ::: "memory")
; #define G_BAR __builtin_amdgcn_s_barrier()
;     ...
;         for (int t = 0; t < nt; t += 2) {
;             const bool last = (t == nt - 2);
;             const char* a1 = cA + (size_t)(t + 1) * ckA;
;             const char* a2 = last ? nA : cA + (size_t)(t + 2) * ckA; const char* b2 = last ? nB : cB + (size_t)(t + 2) * kB;
;             const char* a3 = a2 + ckA; const char* b3 = b2 + kB;
;             G_LDB(B0, 0, 0); G_SCHED; G_LDA(At, 0, 0); G_STAGE(G_SA(1, 1), a1 + chA, cA0, qA);
;             G_WAIT_L(8); G_BAR; G_WAIT_L(0); G_MMA(0, 0, At, B0); G_BAR; G_SCHED;
;             G_LDB(B1, 0, 1); G_STAGE(G_SB(0, 0), b2, cB0, qB);
;             G_BAR; G_WAIT_L(0); G_MMA(0, 1, At, B1); G_BAR;
;             G_LDA(At, 0, 1); G_STAGE(G_SA(0, 0), a2, cA0, qA);
;             G_BAR; G_WAIT_L(0); G_MMA(1, 0, At, B0); G_BAR; G_SCHED;
;             G_STAGE(G_SB(0, 1), b2 + chB, cB0, qB);
;             G_WAIT_V(6); G_BAR; G_MMA(1, 1, At, B1); G_BAR;
;             G_LDB(B0, 1, 0); G_SCHED; G_LDA(At, 1, 0); G_STAGE(G_SA(0, 1), a2 + chA, cA0, qA);
;             G_WAIT_L(8); G_BAR; G_WAIT_L(0); G_MMA(0, 0, At, B0); G_BAR; G_SCHED;
;             G_LDB(B1, 1, 1); G_STAGE(G_SB(1, 0), b3, cB0, qB);
;             G_BAR; G_WAIT_L(0); G_MMA(0, 1, At, B1); G_BAR;
;             G_LDA(At, 1, 1); G_STAGE(G_SA(1, 0), a3, cA0, qA);
;             G_BAR; G_WAIT_L(0); G_MMA(1, 0, At, B0); G_BAR; G_SCHED;
;             G_STAGE(G_SB(1, 1), b3 + chB, cB0, qB);
;             G_WAIT_V(6); G_BAR; G_MMA(1, 1, At, B1); G_BAR;
	s_waitcnt lgkmcnt(0)
	v_mfma_f32_16x16x32_bf16 v[140:143], v[64:67], v[152:155], v[140:143]
	v_mfma_f32_16x16x32_bf16 v[136:139], v[144:147], v[152:155], v[136:139]
	v_mfma_f32_16x16x32_bf16 v[124:127], v[64:67], v[162:165], v[124:127]
	v_mfma_f32_16x16x32_bf16 v[120:123], v[144:147], v[162:165], v[120:123]
	v_mfma_f32_16x16x32_bf16 v[108:111], v[64:67], v[176:179], v[108:111]
	v_mfma_f32_16x16x32_bf16 v[104:107], v[144:147], v[176:179], v[104:107]
	v_mfma_f32_16x16x32_bf16 v[92:95], v[64:67], v[200:203], v[92:95]
	v_mfma_f32_16x16x32_bf16 v[88:91], v[144:147], v[200:203], v[88:91]
	v_mfma_f32_16x16x32_bf16 v[140:143], v[68:71], v[156:159], v[140:143]
	v_mfma_f32_16x16x32_bf16 v[136:139], v[148:151], v[156:159], v[136:139]
	v_mfma_f32_16x16x32_bf16 v[124:127], v[68:71], v[172:175], v[124:127]
	v_mfma_f32_16x16x32_bf16 v[120:123], v[148:151], v[172:175], v[120:123]
	v_mfma_f32_16x16x32_bf16 v[108:111], v[68:71], v[196:199], v[108:111]
	v_mfma_f32_16x16x32_bf16 v[104:107], v[148:151], v[196:199], v[104:107]
	v_mfma_f32_16x16x32_bf16 v[92:95], v[68:71], v[204:207], v[92:95]
	v_mfma_f32_16x16x32_bf16 v[88:91], v[148:151], v[204:207], v[88:91]
	s_barrier
	s_mov_b32 m0, s30
	ds_read_b128 v[208:211], v255 offset:49152
	ds_read_b128 v[212:215], v255 offset:50176
	ds_read_b128 v[216:219], v255 offset:51200
	ds_read_b128 v[220:223], v255 offset:52224
	s_add_u32 vcc_lo, s26, s46
	s_addc_u32 vcc_hi, s27, s47
	global_load_lds_dwordx4 v2, vcc
	s_mov_b32 m0, s67
	s_add_u32 vcc_lo, s26, s70
	s_addc_u32 vcc_hi, s27, s71
	global_load_lds_dwordx4 v2, vcc
	s_barrier
	s_waitcnt lgkmcnt(0)
	v_mfma_f32_16x16x32_bf16 v[132:135], v[208:211], v[152:155], v[132:135]
	v_mfma_f32_16x16x32_bf16 v[128:131], v[216:219], v[152:155], v[128:131]
	v_mfma_f32_16x16x32_bf16 v[116:119], v[208:211], v[162:165], v[116:119]
	v_mfma_f32_16x16x32_bf16 v[112:115], v[216:219], v[162:165], v[112:115]
	v_mfma_f32_16x16x32_bf16 v[100:103], v[208:211], v[176:179], v[100:103]
	v_mfma_f32_16x16x32_bf16 v[96:99], v[216:219], v[176:179], v[96:99]
	v_mfma_f32_16x16x32_bf16 v[84:87], v[208:211], v[200:203], v[84:87]
	v_mfma_f32_16x16x32_bf16 v[80:83], v[216:219], v[200:203], v[80:83]
	v_mfma_f32_16x16x32_bf16 v[132:135], v[212:215], v[156:159], v[132:135]
	v_mfma_f32_16x16x32_bf16 v[128:131], v[220:223], v[156:159], v[128:131]
	v_mfma_f32_16x16x32_bf16 v[116:119], v[212:215], v[172:175], v[116:119]
	v_mfma_f32_16x16x32_bf16 v[112:115], v[220:223], v[172:175], v[112:115]
	v_mfma_f32_16x16x32_bf16 v[100:103], v[212:215], v[196:199], v[100:103]
	v_mfma_f32_16x16x32_bf16 v[96:99], v[220:223], v[196:199], v[96:99]
	v_mfma_f32_16x16x32_bf16 v[84:87], v[212:215], v[204:207], v[84:87]
	v_mfma_f32_16x16x32_bf16 v[80:83], v[220:223], v[204:207], v[80:83]
	s_barrier
	s_mov_b32 m0, s53
	ds_read_b128 v[152:155], v184 offset:49152
	ds_read_b128 v[156:159], v184 offset:50176
	ds_read_b128 v[162:165], v184 offset:51200
	ds_read_b128 v[172:175], v184 offset:52224
	ds_read_b128 v[176:179], v184 offset:53248
	ds_read_b128 v[196:199], v184 offset:54272
	ds_read_b128 v[200:203], v184 offset:55296
	ds_read_b128 v[204:207], v184 offset:56320
	s_add_u32 vcc_lo, s34, s46
	s_addc_u32 vcc_hi, s35, s47
	global_load_lds_dwordx4 v160, vcc
	s_mov_b32 m0, s54
	s_add_u32 vcc_lo, s34, s68
	s_addc_u32 vcc_hi, s35, s69
	global_load_lds_dwordx4 v160, vcc
	s_barrier
	s_waitcnt lgkmcnt(0)
	v_mfma_f32_16x16x32_bf16 v[76:79], v[64:67], v[152:155], v[76:79]
	v_mfma_f32_16x16x32_bf16 v[72:75], v[144:147], v[152:155], v[72:75]
	v_mfma_f32_16x16x32_bf16 v[52:55], v[64:67], v[162:165], v[52:55]
	v_mfma_f32_16x16x32_bf16 v[48:51], v[144:147], v[162:165], v[48:51]
	v_mfma_f32_16x16x32_bf16 v[36:39], v[64:67], v[176:179], v[36:39]
	v_mfma_f32_16x16x32_bf16 v[32:35], v[144:147], v[176:179], v[32:35]
	v_mfma_f32_16x16x32_bf16 v[20:23], v[64:67], v[200:203], v[20:23]
	v_mfma_f32_16x16x32_bf16 v[16:19], v[144:147], v[200:203], v[16:19]
	v_mfma_f32_16x16x32_bf16 v[76:79], v[68:71], v[156:159], v[76:79]
	v_mfma_f32_16x16x32_bf16 v[72:75], v[148:151], v[156:159], v[72:75]
	v_mfma_f32_16x16x32_bf16 v[52:55], v[68:71], v[172:175], v[52:55]
	v_mfma_f32_16x16x32_bf16 v[48:51], v[148:151], v[172:175], v[48:51]
	v_mfma_f32_16x16x32_bf16 v[36:39], v[68:71], v[196:199], v[36:39]
	v_mfma_f32_16x16x32_bf16 v[32:35], v[148:151], v[196:199], v[32:35]
	v_mfma_f32_16x16x32_bf16 v[20:23], v[68:71], v[204:207], v[20:23]
	v_mfma_f32_16x16x32_bf16 v[16:19], v[148:151], v[204:207], v[16:19]
	s_barrier
	s_mov_b32 m0, s65
	s_add_u32 vcc_lo, s26, s84
	s_addc_u32 vcc_hi, s27, s85
	global_load_lds_dwordx4 v2, vcc
	s_mov_b32 m0, s64
	s_add_u32 vcc_lo, s26, s28
	s_addc_u32 vcc_hi, s27, s29
	global_load_lds_dwordx4 v2, vcc
	s_waitcnt vmcnt(6)
	s_barrier
	v_mfma_f32_16x16x32_bf16 v[56:59], v[208:211], v[152:155], v[56:59]
	v_mfma_f32_16x16x32_bf16 v[68:71], v[212:215], v[156:159], v[56:59]
	v_mfma_f32_16x16x32_bf16 v[56:59], v[216:219], v[152:155], v[60:63]
	v_mfma_f32_16x16x32_bf16 v[44:47], v[208:211], v[162:165], v[44:47]
	v_mfma_f32_16x16x32_bf16 v[40:43], v[216:219], v[162:165], v[40:43]
	v_mfma_f32_16x16x32_bf16 v[28:31], v[208:211], v[176:179], v[28:31]
	v_mfma_f32_16x16x32_bf16 v[24:27], v[216:219], v[176:179], v[24:27]
	v_mfma_f32_16x16x32_bf16 v[12:15], v[208:211], v[200:203], v[12:15]
	v_mfma_f32_16x16x32_bf16 v[8:11], v[216:219], v[200:203], v[8:11]
	v_mfma_f32_16x16x32_bf16 v[64:67], v[220:223], v[156:159], v[56:59]
	v_mfma_f32_16x16x32_bf16 v[44:47], v[212:215], v[172:175], v[44:47]
	v_mfma_f32_16x16x32_bf16 v[40:43], v[220:223], v[172:175], v[40:43]
	v_mfma_f32_16x16x32_bf16 v[28:31], v[212:215], v[196:199], v[28:31]
	v_mfma_f32_16x16x32_bf16 v[24:27], v[220:223], v[196:199], v[24:27]
	v_mfma_f32_16x16x32_bf16 v[12:15], v[212:215], v[204:207], v[12:15]
	v_mfma_f32_16x16x32_bf16 v[8:11], v[220:223], v[204:207], v[8:11]
	s_andn2_b64 vcc, exec, s[24:25]
	s_mov_b64 s[26:27], -1
	s_mov_b64 s[24:25], 0
	s_mov_b64 s[30:31], 0x100
	s_cbranch_vccz .Ldb_SSM2_cont
